# grid barrier release flattened: the last-arriving XCD leader bumps every XCC's generation word itself (16 atomics) instead of top-generation -> other leaders -> their generation words; non-last leader
# speedup vs baseline: 1.0082x; 1.0082x over previous
.LBB0_2142:
	s_or_b64 exec, exec, s[2:3]
	s_and_saveexec_b64 s[2:3], s[4:5]
	s_cbranch_execz .LBB0_2144
	global_atomic_add v[0:1], v197, off
	s_add_u32 s10, s84, 0x2200
	s_addc_u32 s11, s85, 0
	global_atomic_add v20, v197, s[10:11]
	global_atomic_add v20, v197, s[10:11] offset:256
	global_atomic_add v20, v197, s[10:11] offset:512
	global_atomic_add v20, v197, s[10:11] offset:768
	global_atomic_add v20, v197, s[10:11] offset:1024
	global_atomic_add v20, v197, s[10:11] offset:1280
	global_atomic_add v20, v197, s[10:11] offset:1536
	global_atomic_add v20, v197, s[10:11] offset:1792
	global_atomic_add v20, v197, s[10:11] offset:2048
	global_atomic_add v20, v197, s[10:11] offset:2304
	global_atomic_add v20, v197, s[10:11] offset:2560
	global_atomic_add v20, v197, s[10:11] offset:2816
	global_atomic_add v20, v197, s[10:11] offset:3072
	global_atomic_add v20, v197, s[10:11] offset:3328
	global_atomic_add v20, v197, s[10:11] offset:3584
	global_atomic_add v20, v197, s[10:11] offset:3840
.LBB0_2144:
	s_or_b64 exec, exec, s[2:3]
	s_mov_b64 s[2:3], exec
	v_mbcnt_lo_u32_b32 v0, s2, 0
	v_mbcnt_hi_u32_b32 v0, s3, v0
	v_cmp_eq_u32_e32 vcc, 0, v0
	s_waitcnt vmcnt(0)
	s_and_saveexec_b64 s[4:5], vcc
	s_cbranch_execz .LBB0_2146
	s_bcnt1_i32_b64 s2, s[2:3]
	v_mov_b32_e32 v0, s2
	v_readlane_b32 s2, v254, 62
	v_readlane_b32 s3, v254, 63
	s_nop 4
.LBB0_2146:
	s_or_b64 exec, exec, s[4:5]
	s_waitcnt vmcnt(0)
